# MLA tile loop back edge rotated (single conditional back branch), on top of v17
# baseline (speedup 1.0000x reference)
; __device__ __forceinline__ void mla_attn_phase(const Ctx&, unsigned char* ws) { const Ctx c = mk_ctx();
;     ...
;         for (int j = 0; j < ntiles; ++j) { bf16* Kb = Kl + (j & 1) * KTILE_E; bf16* Vb = Vl + (j & 1) * VTILE_E;
;             *(v4u*)(Kb + kc0_row * KLD + kc0_part * 8) = kreg0; if (tid < 256) *(v4u*)(Kb + kc1_row * KLD + kc1_part * 8) = kreg1;
;             *(v2u*)(Vb + vd * VLD + vpart * 8) = (v2u){vreg.x, vreg.y}; *(v2u*)(Vb + vd * VLD + vpart * 8 + 4) = (v2u){vreg.z, vreg.w};
;             __syncthreads();
;             if (j + 1 < ntiles) MLA_LOAD(j + 1);
;             if (j <= my_last) {
.LBB0_755:
	v_subrev_u32_e32 v187, 64, v187
	s_add_i32 s37, s37, 64
	v_lshl_add_u64 v[136:137], v[136:137], 0, s[94:95]
	v_lshl_add_u64 v[138:139], v[138:139], 0, v[140:141]
	v_lshl_add_u64 v[142:143], v[142:143], 0, v[144:145]
	s_and_b64 vcc, exec, s[24:25]
	s_mov_b32 s41, s38
	s_cbranch_vccz .LBB0_745
	s_branch .LBB0_727
